# loop-edge: 64-byte alignment of the NSA-phase inner loop heads (score, top-k, selected, window loops) plus K-loop and pool-fold heads
# speedup vs baseline: 1.0050x; 1.0050x over previous
; DI unsigned cvtpk(float lo, float hi) { return pg8::cvt_pk_bf16(lo, hi); }
; #define LDS_FENCE() asm volatile("s_waitcnt lgkmcnt(0)" ::: "memory")
; DI void tr_tile(const float* __restrict__ src, int srcN, int k0, int n0, int mode, const float* __restrict__ gk, bf16_t* dst, size_t dpitch, int ncopies, float* scr, int lane) {
;     ...
;     for (int i = 0; i < 32; ++i) { const int kk = 2 * i + (lane >> 5); float v = v32[i]; if (gk) v *= gk[k0 + kk]; scr[kk * 33 + nn] = v; }
;     LDS_FENCE();
;     const int c = lane & 7;
; #pragma unroll
;     for (int j = 0; j < 4; ++j) { const int nr = (lane >> 3) + 8 * j; const float* s = scr + (8 * c) * 33 + nr; const int drow = n0 + nr;
;         u32x4 o; o.x = cvtpk(s[0], s[33]); o.y = cvtpk(s[2 * 33], s[3 * 33]); o.z = cvtpk(s[4 * 33], s[5 * 33]); o.w = cvtpk(s[6 * 33], s[7 * 33]);
;         const bool skip = (mode == 1) && drow >= C_PL && drow < C_PL + 512;
;         if (!skip) for (int cp = 0; cp < ncopies; ++cp) *(u32x4*)(dst + (size_t)drow * dpitch + cp * 1024 + k0 + 8 * c) = o; }
;     LDS_FENCE();
.LBB0_278:
	s_ashr_i32 s15, s14, 31
	s_waitcnt vmcnt(3)
	v_mov_b32_e32 v10, v8
	s_waitcnt vmcnt(2)
	v_mov_b32_e32 v11, v9
	s_waitcnt vmcnt(1)
	v_mov_b32_e32 v12, v6
	s_waitcnt vmcnt(0)
	v_mov_b32_e32 v13, v7
	ds_write_b32 v58, v66
	ds_write_b32 v59, v67
	ds_write_b32 v60, v68
	ds_write_b32 v61, v69
.LBB0_279:
	s_waitcnt vmcnt(9)
	ds_write_b32 v62, v10
	s_waitcnt vmcnt(8)
	ds_write_b32 v63, v11
	ds_write_b32 v64, v12
	ds_write_b32 v65, v13
	s_waitcnt lgkmcnt(0)
	ds_read2_b32 v[12:13], v31 offset0:33 offset1:41
	ds_read2_b32 v[14:15], v31 offset1:8
	ds_read2_b32 v[16:17], v31 offset0:66 offset1:74
	ds_read2_b32 v[18:19], v31 offset0:99 offset1:107
	ds_read2_b32 v[20:21], v31 offset0:132 offset1:140
	ds_read2_b32 v[22:23], v31 offset0:165 offset1:173
	ds_read2_b32 v[24:25], v31 offset0:198 offset1:206
	s_waitcnt vmcnt(6)
	ds_read2_b32 v[66:67], v31 offset0:231 offset1:239
	s_waitcnt vmcnt(5)
	v_add_u32_e32 v68, s25, v30
	s_waitcnt vmcnt(4)
	v_ashrrev_i32_e32 v69, 31, v68
	v_lshl_add_u64 v[10:11], s[14:15], 1, v[4:5]
	v_lshlrev_b64 v[70:71], 11, v[68:69]
	s_waitcnt vmcnt(1) lgkmcnt(6)
	v_cvt_pk_bf16_f32 v6, v14, v12
	s_waitcnt vmcnt(0) lgkmcnt(4)
	v_cvt_pk_bf16_f32 v7, v16, v18
	s_waitcnt lgkmcnt(2)
	v_cvt_pk_bf16_f32 v8, v20, v22
	s_waitcnt lgkmcnt(0)
	v_cvt_pk_bf16_f32 v9, v24, v66
	v_lshl_add_u64 v[70:71], v[10:11], 0, v[70:71]
	v_add_u32_e32 v12, 8, v68
	global_store_dwordx4 v[70:71], v[6:9], off
	v_add_u32_e32 v70, 16, v68
	v_ashrrev_i32_e32 v71, 31, v70
	v_cvt_pk_bf16_f32 v6, v15, v13
	v_ashrrev_i32_e32 v13, 31, v12
	v_lshlrev_b64 v[12:13], 11, v[12:13]
	v_cvt_pk_bf16_f32 v7, v17, v19
	v_cvt_pk_bf16_f32 v8, v21, v23
	v_cvt_pk_bf16_f32 v9, v25, v67
	v_lshl_add_u64 v[12:13], v[10:11], 0, v[12:13]
	global_store_dwordx4 v[12:13], v[6:9], off
	ds_read2_b32 v[12:13], v31 offset0:49 offset1:57
	ds_read2_b32 v[14:15], v31 offset0:16 offset1:24
	ds_read2_b32 v[16:17], v31 offset0:82 offset1:90
	ds_read2_b32 v[18:19], v31 offset0:115 offset1:123
	ds_read2_b32 v[20:21], v31 offset0:148 offset1:156
	ds_read2_b32 v[22:23], v31 offset0:181 offset1:189
	ds_read2_b32 v[24:25], v31 offset0:214 offset1:222
	ds_read2_b32 v[66:67], v31 offset0:247 offset1:255
	v_lshlrev_b64 v[70:71], 11, v[70:71]
	s_waitcnt lgkmcnt(6)
	v_cvt_pk_bf16_f32 v6, v14, v12
	s_waitcnt lgkmcnt(4)
	v_cvt_pk_bf16_f32 v7, v16, v18
	s_waitcnt lgkmcnt(2)
	v_cvt_pk_bf16_f32 v8, v20, v22
	s_waitcnt lgkmcnt(0)
	v_cvt_pk_bf16_f32 v9, v24, v66
	v_lshl_add_u64 v[70:71], v[10:11], 0, v[70:71]
	v_add_u32_e32 v12, 24, v68
	global_store_dwordx4 v[70:71], v[6:9], off
	s_nop 1
	v_cvt_pk_bf16_f32 v6, v15, v13
	v_ashrrev_i32_e32 v13, 31, v12
	v_lshlrev_b64 v[12:13], 11, v[12:13]
	v_cvt_pk_bf16_f32 v7, v17, v19
	v_cvt_pk_bf16_f32 v8, v21, v23
	v_cvt_pk_bf16_f32 v9, v25, v67
	v_lshl_add_u64 v[10:11], v[10:11], 0, v[12:13]
	global_store_dwordx4 v[10:11], v[6:9], off
	s_waitcnt lgkmcnt(0)
	.p2align	6
